# speedup vs baseline: 1.0020x; 1.0020x over previous
; #define LAS __attribute__((address_space(3)))
; __device__ __forceinline__ void attn_unit(LAS unsigned char* lds, bf16_t* Qm, const bf16_t* __restrict__ Kb, const bf16_t* __restrict__ Vt,
;                                           int b, int h, int qb, int lgS, float lam, float oscale, const float* __restrict__ subg, float* stash) {
;     ...
;             for (int b2 = 0; b2 < 4; ++b2) vfb[b2] = *(const LAS bf16x8*)(lds + vs0 + vr + b2 * 32 * VP + 32);
;     ...
;                         for (int b2 = 0; b2 < 4; ++b2) { const bf16x8 v_ = *(const LAS bf16x8*)(lds + vs0 + vr + b2 * 32 * VP + (ks + 1) * 32); if (ks & 1) vfa[b2] = v_; else vfb[b2] = v_; }
.Lmy_noprio:
	v_add_u32_e32 v251, s28, v220

; #define LAS __attribute__((address_space(3)))
; #define ATT_SB() __builtin_amdgcn_sched_barrier(0)
; __device__ __forceinline__ void attn_unit(LAS unsigned char* lds, bf16_t* Qm, const bf16_t* __restrict__ Kb, const bf16_t* __restrict__ Vt,
;                                           int b, int h, int qb, int lgS, float lam, float oscale, const float* __restrict__ subg, float* stash) {
;     ...
;             for (int b2 = 0; b2 < 4; ++b2) vfb[b2] = *(const LAS bf16x8*)(lds + vs0 + vr + b2 * 32 * VP + 32);
;             float mxa, mxb;
;             o[0] = __builtin_amdgcn_mfma_f32_32x32x16_bf16(vfa[0], __builtin_bit_cast(bf16x8, pk[0]), o[0], 0, 0, 0);
;             mxa = ATT_MX3(p0[0], p0[1], p1[0]); mxb = ATT_MX3(p0[2], p0[3], p1[1]); mxa = ATT_MX3(mxa, p1[2], p1[3]); mxa = ATT_MX3(mxa, p0[4], p0[5]); mxb = ATT_MX3(mxb, p0[6], p0[7]);
;             ATT_SB();
;             o[1] = __builtin_amdgcn_mfma_f32_32x32x16_bf16(vfa[1], __builtin_bit_cast(bf16x8, pk[0]), o[1], 0, 0, 0);
;             mxa = ATT_MX3(mxa, p1[4], p1[5]); mxb = ATT_MX3(mxb, p1[6], p1[7]); mxa = ATT_MX3(mxa, p0[8], p0[9]); mxb = ATT_MX3(mxb, p0[10], p0[11]); mxa = ATT_MX3(mxa, p1[8], p1[9]);
;             ATT_SB();
;             o[2] = __builtin_amdgcn_mfma_f32_32x32x16_bf16(vfa[2], __builtin_bit_cast(bf16x8, pk[0]), o[2], 0, 0, 0);
;             mxb = ATT_MX3(mxb, p1[10], p1[11]); mxa = ATT_MX3(mxa, p0[12], p0[13]); mxb = ATT_MX3(mxb, p0[14], p0[15]); mxa = ATT_MX3(mxa, p1[12], p1[13]); mxb = ATT_MX3(mxb, p1[14], p1[15]);
;             ATT_SB();
;             o[3] = __builtin_amdgcn_mfma_f32_32x32x16_bf16(vfa[3], __builtin_bit_cast(bf16x8, pk[0]), o[3], 0, 0, 0);
;             float mx;
;             { const float m_ = __builtin_fmaxf(mxa, mxb); auto rr_ = __builtin_amdgcn_permlane32_swap(__float_as_uint(m_), __float_as_uint(m_), false, false);
;               mx = __builtin_fmaxf(__uint_as_float(rr_[0]), __uint_as_float(rr_[1])); }
;             ATT_SB();
;             if (__builtin_expect(__any(mx > 8.0f), 0)) {
;                 const float dl = (mx > 8.0f) ? mx : 0.f;
;                 mhat += dl;
; #pragma unroll
;                 for (int r = 0; r < 16; ++r) { p0[r] -= dl; p1[r] -= dl; }
;                 const float f = __builtin_amdgcn_exp2f(-dl);
;                 lrun *= f;
; #pragma unroll
;                 for (int i = 0; i < 4; ++i) o[i] = o[i] * f;
; #pragma unroll
.Lmy_skip_vl:
	v_mfma_f32_32x32x16_bf16 v[80:95], v[216:219], v[144:147], v[80:95]
	ds_read_b128 v[216:219], v251 offset:25376
	ds_read_b128 v[212:215], v251 offset:29984
	ds_read_b128 v[208:211], v251 offset:34592
	ds_read_b128 v[204:207], v251 offset:39200
	v_mfma_f32_32x32x16_bf16 v[96:111], v[222:225], v[148:151], v[96:111]
	v_mfma_f32_32x32x16_bf16 v[80:95], v[240:243], v[148:151], v[80:95]
	s_nop 10
	v_max_f32_e32 v222, v96, v97
	v_mfma_f32_32x32x16_bf16 v[0:15], v[196:199], v[200:203], v[0:15]
	v_max3_f32 v223, v98, v99, v81
	v_max3_f32 v222, v222, v80, v82
	v_max3_f32 v222, v222, v83, v100
	v_max3_f32 v223, v223, v102, v103
	v_mfma_f32_32x32x16_bf16 v[48:63], v[192:195], v[200:203], v[48:63]
	v_max3_f32 v192, v222, v101, v84
	v_max3_f32 v193, v223, v86, v87
	v_max3_f32 v192, v192, v85, v104
	v_max3_f32 v193, v193, v106, v107
	v_max3_f32 v192, v192, v105, v88
	v_mfma_f32_32x32x16_bf16 v[32:47], v[188:191], v[200:203], v[32:47]
	v_max3_f32 v188, v193, v90, v91
	v_max3_f32 v189, v192, v89, v108
	v_max3_f32 v188, v188, v110, v111
	v_max3_f32 v189, v189, v109, v92
	v_max3_f32 v188, v188, v94, v95
	v_mfma_f32_32x32x16_bf16 v[16:31], v[184:187], v[200:203], v[16:31]
	v_max3_f32 v184, v189, v93, v188
	v_mov_b32_e32 v185, v184
	s_nop 1
	v_permlane32_swap_b32_e32 v184, v185
	v_max_f32_e32 v184, v184, v185
	s_mov_b32 s30, 0x41000000
	v_cmp_lt_f32_e32 vcc, s30, v184
	s_cbranch_vccnz .LBB0_348
.LBB0_342:
	v_exp_f32_e32 v96, v96
	s_waitcnt lgkmcnt(3)
	v_mfma_f32_32x32x16_bf16 v[0:15], v[216:219], v[180:183], v[0:15]
	v_exp_f32_e32 v97, v97
	ds_read_b128 v[192:195], v251 offset:25408
	ds_read_b128 v[196:199], v251 offset:30016
	ds_read_b128 v[188:191], v251 offset:34624
	ds_read_b128 v[184:187], v251 offset:39232
	v_exp_f32_e32 v88, v88
	v_exp_f32_e32 v89, v89
	v_add_f32_e32 v200, v96, v97
	s_nop 0
	v_add_f32_e32 v200, v88, v200
	v_add_f32_e32 v200, v89, v200
	v_exp_f32_e32 v98, v98
	s_waitcnt lgkmcnt(6)
	v_mfma_f32_32x32x16_bf16 v[48:63], v[212:215], v[180:183], v[48:63]
	v_exp_f32_e32 v99, v99
	v_exp_f32_e32 v90, v90
	v_add_f32_e32 v200, v98, v200
	v_exp_f32_e32 v91, v91
	v_add_f32_e32 v200, v99, v200
	s_nop 0
	v_add_f32_e32 v200, v90, v200
	v_add_f32_e32 v200, v91, v200
	v_exp_f32_e32 v100, v100
	s_waitcnt lgkmcnt(5)
	v_mfma_f32_32x32x16_bf16 v[32:47], v[208:211], v[180:183], v[32:47]
	v_exp_f32_e32 v101, v101
	v_exp_f32_e32 v92, v92
	v_add_f32_e32 v200, v100, v200
	v_exp_f32_e32 v93, v93
	v_add_f32_e32 v200, v101, v200
	s_nop 0
	v_add_f32_e32 v200, v92, v200
	v_add_f32_e32 v200, v93, v200
	v_exp_f32_e32 v102, v102
	s_waitcnt lgkmcnt(4)
	v_mfma_f32_32x32x16_bf16 v[16:31], v[204:207], v[180:183], v[16:31]
	v_exp_f32_e32 v103, v103
	v_exp_f32_e32 v94, v94
	v_add_f32_e32 v180, v102, v200
	v_exp_f32_e32 v95, v95
	v_add_f32_e32 v180, v103, v180
	s_nop 0
	v_add_f32_e32 v180, v94, v180
	v_add_f32_e32 v212, v95, v180
	s_waitcnt lgkmcnt(3)
	v_mfma_f32_32x32x16_bf16 v[0:15], v[192:195], v[172:175], v[0:15]
	ds_read_b128 v[180:183], v251 offset:25440
	ds_read_b128 v[200:203], v251 offset:30048
	ds_read_b128 v[204:207], v251 offset:34656
	ds_read_b128 v[208:211], v251 offset:39264
	v_exp_f32_e32 v104, v104
	v_exp_f32_e32 v105, v105
	v_add_f32_e32 v156, v104, v212
	v_add_f32_e32 v156, v105, v156
	v_add_u32_e32 v251, s25, v220
	v_add_u32_e32 v160, s50, v235
	s_waitcnt lgkmcnt(6)
	v_mfma_f32_32x32x16_bf16 v[48:63], v[196:199], v[172:175], v[48:63]
	ds_read_b128 v[192:195], v251 offset:29952
	v_exp_f32_e32 v106, v106
	v_exp_f32_e32 v107, v107
	v_add_f32_e32 v156, v106, v156
	v_add_f32_e32 v156, v107, v156
	s_cmp_eq_u32 s98, 0
	s_cbranch_scc1 .Lmy_skip_m
	s_waitcnt lgkmcnt(1)
	s_barrier
